# P1 C-tile epilogue hand-written: bf16 tile staged through LDS as row pairs and written with 16-byte full-line stores
# speedup vs baseline: 1.0215x; 1.0025x over previous
.Lp1m_kloop:
	s_waitcnt vmcnt(0) lgkmcnt(0)
	s_barrier
	ds_read_b128 v[170:173], v232 offset:24576
	ds_read_b128 v[174:177], v232 offset:26624
	ds_read_b128 v[178:181], v230 offset:24576
	ds_read_b128 v[182:185], v230 offset:26624
	ds_read_b128 v[186:189], v230 offset:28672
	ds_read_b128 v[190:193], v230 offset:30720
	s_setprio 1
	v_mfma_f32_32x32x16_bf16 v[48:63], v[222:225], v[206:209], v[48:63]
	v_mfma_f32_32x32x16_bf16 v[32:47], v[222:225], v[210:213], v[32:47]
	v_mfma_f32_32x32x16_bf16 v[16:31], v[226:229], v[206:209], v[16:31]
	v_mfma_f32_32x32x16_bf16 v[0:15], v[226:229], v[210:213], v[0:15]
	s_setprio 0
	s_add_u32 m0, s101, 0xc000
	s_nop 0
	global_load_lds_dwordx4 v234, s[98:99]
	s_add_u32 m0, s101, 0x0
	s_nop 0
	global_load_lds_dwordx4 v234, s[44:45]
	s_add_u32 m0, s101, 0xc400
	s_nop 0
	global_load_lds_dwordx4 v235, s[98:99]
	s_add_u32 m0, s101, 0x400
	s_nop 0
	global_load_lds_dwordx4 v235, s[44:45]
	s_waitcnt lgkmcnt(2)
	s_setprio 1
	v_mfma_f32_32x32x16_bf16 v[112:127], v[178:181], v[170:173], v[112:127]
	v_mfma_f32_32x32x16_bf16 v[96:111], v[178:181], v[174:177], v[96:111]
	v_mfma_f32_32x32x16_bf16 v[80:95], v[182:185], v[170:173], v[80:95]
	v_mfma_f32_32x32x16_bf16 v[64:79], v[182:185], v[174:177], v[64:79]
	s_setprio 0
	ds_read_b128 v[206:209], v233 offset:24576
	ds_read_b128 v[210:213], v233 offset:26624
	ds_read_b128 v[214:217], v231 offset:24576
	ds_read_b128 v[218:221], v231 offset:26624
	s_add_u32 m0, s101, 0xc800
	s_nop 0
	global_load_lds_dwordx4 v236, s[98:99]
	s_add_u32 m0, s101, 0x800
	s_nop 0
	global_load_lds_dwordx4 v236, s[44:45]
	s_add_u32 m0, s101, 0xcc00
	s_nop 0
	global_load_lds_dwordx4 v237, s[98:99]
	s_add_u32 m0, s101, 0xc00
	s_nop 0
	global_load_lds_dwordx4 v237, s[44:45]
	s_waitcnt lgkmcnt(4)
	s_setprio 1
	v_mfma_f32_32x32x16_bf16 v[48:63], v[186:189], v[170:173], v[48:63]
	v_mfma_f32_32x32x16_bf16 v[32:47], v[186:189], v[174:177], v[32:47]
	v_mfma_f32_32x32x16_bf16 v[16:31], v[190:193], v[170:173], v[16:31]
	v_mfma_f32_32x32x16_bf16 v[0:15], v[190:193], v[174:177], v[0:15]
	s_setprio 0
	ds_read_b128 v[222:225], v231 offset:28672
	ds_read_b128 v[226:229], v231 offset:30720
	v_xad_u32 v241, s36, v240, v238
	v_xad_u32 v242, s37, v240, v239
	s_add_u32 m0, s49, 0xc000
	s_nop 0
	global_load_lds_dwordx4 v241, s[94:95]
	s_add_u32 m0, s49, 0xffffffc0
	s_nop 0
	global_load_lds_dwordx4 v241, s[94:95] offset:64
	s_add_u32 m0, s49, 0xc400
	s_nop 0
	global_load_lds_dwordx4 v242, s[94:95]
	s_add_u32 m0, s49, 0x3c0
	s_nop 0
	global_load_lds_dwordx4 v242, s[94:95] offset:64
	s_add_u32 s36, s36, 0x80
	s_xor_b32 s37, s36, 0x800
	s_add_u32 s98, s98, 128
	s_addc_u32 s99, s99, 0
	s_add_u32 s44, s44, 128
	s_addc_u32 s45, s45, 0
	s_waitcnt lgkmcnt(2)
	s_setprio 1
	v_mfma_f32_32x32x16_bf16 v[112:127], v[214:217], v[206:209], v[112:127]
	v_mfma_f32_32x32x16_bf16 v[96:111], v[214:217], v[210:213], v[96:111]
	v_mfma_f32_32x32x16_bf16 v[80:95], v[218:221], v[206:209], v[80:95]
	v_mfma_f32_32x32x16_bf16 v[64:79], v[218:221], v[210:213], v[64:79]
	s_setprio 0
	s_waitcnt vmcnt(0) lgkmcnt(0)
	s_barrier
	ds_read_b128 v[170:173], v232 offset:49152
	ds_read_b128 v[174:177], v232 offset:51200
	ds_read_b128 v[178:181], v230 offset:49152
	ds_read_b128 v[182:185], v230 offset:51200
	ds_read_b128 v[186:189], v230 offset:53248
	ds_read_b128 v[190:193], v230 offset:55296
	s_setprio 1
	v_mfma_f32_32x32x16_bf16 v[48:63], v[222:225], v[206:209], v[48:63]
	v_mfma_f32_32x32x16_bf16 v[32:47], v[222:225], v[210:213], v[32:47]
	v_mfma_f32_32x32x16_bf16 v[16:31], v[226:229], v[206:209], v[16:31]
	v_mfma_f32_32x32x16_bf16 v[0:15], v[226:229], v[210:213], v[0:15]
	s_setprio 0
	s_waitcnt lgkmcnt(2)
	s_setprio 1
	v_mfma_f32_32x32x16_bf16 v[112:127], v[178:181], v[170:173], v[112:127]
	v_mfma_f32_32x32x16_bf16 v[96:111], v[178:181], v[174:177], v[96:111]
	v_mfma_f32_32x32x16_bf16 v[80:95], v[182:185], v[170:173], v[80:95]
	v_mfma_f32_32x32x16_bf16 v[64:79], v[182:185], v[174:177], v[64:79]
	s_setprio 0
	ds_read_b128 v[206:209], v233 offset:49152
	ds_read_b128 v[210:213], v233 offset:51200
	ds_read_b128 v[214:217], v231 offset:49152
	ds_read_b128 v[218:221], v231 offset:51200
	s_waitcnt lgkmcnt(4)
	s_setprio 1
	v_mfma_f32_32x32x16_bf16 v[48:63], v[186:189], v[170:173], v[48:63]
	v_mfma_f32_32x32x16_bf16 v[32:47], v[186:189], v[174:177], v[32:47]
	v_mfma_f32_32x32x16_bf16 v[16:31], v[190:193], v[170:173], v[16:31]
	v_mfma_f32_32x32x16_bf16 v[0:15], v[190:193], v[174:177], v[0:15]
	s_setprio 0
	ds_read_b128 v[222:225], v231 offset:53248
	ds_read_b128 v[226:229], v231 offset:55296
	s_waitcnt lgkmcnt(2)
	s_setprio 1
	v_mfma_f32_32x32x16_bf16 v[112:127], v[214:217], v[206:209], v[112:127]
	v_mfma_f32_32x32x16_bf16 v[96:111], v[214:217], v[210:213], v[96:111]
	v_mfma_f32_32x32x16_bf16 v[80:95], v[218:221], v[206:209], v[80:95]
	v_mfma_f32_32x32x16_bf16 v[64:79], v[218:221], v[210:213], v[64:79]
	s_setprio 0
	s_waitcnt vmcnt(0) lgkmcnt(0)
	s_barrier
	ds_read_b128 v[170:173], v232 offset:0
	ds_read_b128 v[174:177], v232 offset:2048
	ds_read_b128 v[178:181], v230 offset:0
	ds_read_b128 v[182:185], v230 offset:2048
	ds_read_b128 v[186:189], v230 offset:4096
	ds_read_b128 v[190:193], v230 offset:6144
	s_setprio 1
	v_mfma_f32_32x32x16_bf16 v[48:63], v[222:225], v[206:209], v[48:63]
	v_mfma_f32_32x32x16_bf16 v[32:47], v[222:225], v[210:213], v[32:47]
	v_mfma_f32_32x32x16_bf16 v[16:31], v[226:229], v[206:209], v[16:31]
	v_mfma_f32_32x32x16_bf16 v[0:15], v[226:229], v[210:213], v[0:15]
	s_setprio 0
	s_add_u32 m0, s101, 0x6000
	s_nop 0
	global_load_lds_dwordx4 v234, s[98:99]
	s_add_u32 m0, s101, 0xc000
	s_nop 0
	global_load_lds_dwordx4 v234, s[44:45]
	s_add_u32 m0, s101, 0x6400
	s_nop 0
	global_load_lds_dwordx4 v235, s[98:99]
	s_add_u32 m0, s101, 0xc400
	s_nop 0
	global_load_lds_dwordx4 v235, s[44:45]
	s_waitcnt lgkmcnt(2)
	s_setprio 1
	v_mfma_f32_32x32x16_bf16 v[112:127], v[178:181], v[170:173], v[112:127]
	v_mfma_f32_32x32x16_bf16 v[96:111], v[178:181], v[174:177], v[96:111]
	v_mfma_f32_32x32x16_bf16 v[80:95], v[182:185], v[170:173], v[80:95]
	v_mfma_f32_32x32x16_bf16 v[64:79], v[182:185], v[174:177], v[64:79]
	s_setprio 0
	ds_read_b128 v[206:209], v233 offset:0
	ds_read_b128 v[210:213], v233 offset:2048
	ds_read_b128 v[214:217], v231 offset:0
	ds_read_b128 v[218:221], v231 offset:2048
	s_add_u32 m0, s101, 0x6800
	s_nop 0
	global_load_lds_dwordx4 v236, s[98:99]
	s_add_u32 m0, s101, 0xc800
	s_nop 0
	global_load_lds_dwordx4 v236, s[44:45]
	s_add_u32 m0, s101, 0x6c00
	s_nop 0
	global_load_lds_dwordx4 v237, s[98:99]
	s_add_u32 m0, s101, 0xcc00
	s_nop 0
	global_load_lds_dwordx4 v237, s[44:45]
	s_waitcnt lgkmcnt(4)
	s_setprio 1
	v_mfma_f32_32x32x16_bf16 v[48:63], v[186:189], v[170:173], v[48:63]
	v_mfma_f32_32x32x16_bf16 v[32:47], v[186:189], v[174:177], v[32:47]
	v_mfma_f32_32x32x16_bf16 v[16:31], v[190:193], v[170:173], v[16:31]
	v_mfma_f32_32x32x16_bf16 v[0:15], v[190:193], v[174:177], v[0:15]
	s_setprio 0
	ds_read_b128 v[222:225], v231 offset:4096
	ds_read_b128 v[226:229], v231 offset:6144
	v_xad_u32 v241, s36, v240, v238
	v_xad_u32 v242, s37, v240, v239
	s_add_u32 m0, s49, 0x6000
	s_nop 0
	global_load_lds_dwordx4 v241, s[94:95]
	s_add_u32 m0, s49, 0xbfc0
	s_nop 0
	global_load_lds_dwordx4 v241, s[94:95] offset:64
	s_add_u32 m0, s49, 0x6400
	s_nop 0
	global_load_lds_dwordx4 v242, s[94:95]
	s_add_u32 m0, s49, 0xc3c0
	s_nop 0
	global_load_lds_dwordx4 v242, s[94:95] offset:64
	s_add_u32 s36, s36, 0x80
	s_xor_b32 s37, s36, 0x800
	s_add_u32 s98, s98, 128
	s_addc_u32 s99, s99, 0
	s_add_u32 s44, s44, 128
	s_addc_u32 s45, s45, 0
	s_waitcnt lgkmcnt(2)
	s_setprio 1
	v_mfma_f32_32x32x16_bf16 v[112:127], v[214:217], v[206:209], v[112:127]
	v_mfma_f32_32x32x16_bf16 v[96:111], v[214:217], v[210:213], v[96:111]
	v_mfma_f32_32x32x16_bf16 v[80:95], v[218:221], v[206:209], v[80:95]
	v_mfma_f32_32x32x16_bf16 v[64:79], v[218:221], v[210:213], v[64:79]
	s_setprio 0
	s_waitcnt vmcnt(0) lgkmcnt(0)
	s_barrier
	ds_read_b128 v[170:173], v232 offset:24576
	ds_read_b128 v[174:177], v232 offset:26624
	ds_read_b128 v[178:181], v230 offset:24576
	ds_read_b128 v[182:185], v230 offset:26624
	ds_read_b128 v[186:189], v230 offset:28672
	ds_read_b128 v[190:193], v230 offset:30720
	s_setprio 1
	v_mfma_f32_32x32x16_bf16 v[48:63], v[222:225], v[206:209], v[48:63]
	v_mfma_f32_32x32x16_bf16 v[32:47], v[222:225], v[210:213], v[32:47]
	v_mfma_f32_32x32x16_bf16 v[16:31], v[226:229], v[206:209], v[16:31]
	v_mfma_f32_32x32x16_bf16 v[0:15], v[226:229], v[210:213], v[0:15]
	s_setprio 0
	s_waitcnt lgkmcnt(2)
	s_setprio 1
	v_mfma_f32_32x32x16_bf16 v[112:127], v[178:181], v[170:173], v[112:127]
	v_mfma_f32_32x32x16_bf16 v[96:111], v[178:181], v[174:177], v[96:111]
	v_mfma_f32_32x32x16_bf16 v[80:95], v[182:185], v[170:173], v[80:95]
	v_mfma_f32_32x32x16_bf16 v[64:79], v[182:185], v[174:177], v[64:79]
	s_setprio 0
	ds_read_b128 v[206:209], v233 offset:24576
	ds_read_b128 v[210:213], v233 offset:26624
	ds_read_b128 v[214:217], v231 offset:24576
	ds_read_b128 v[218:221], v231 offset:26624
	s_waitcnt lgkmcnt(4)
	s_setprio 1
	v_mfma_f32_32x32x16_bf16 v[48:63], v[186:189], v[170:173], v[48:63]
	v_mfma_f32_32x32x16_bf16 v[32:47], v[186:189], v[174:177], v[32:47]
	v_mfma_f32_32x32x16_bf16 v[16:31], v[190:193], v[170:173], v[16:31]
	v_mfma_f32_32x32x16_bf16 v[0:15], v[190:193], v[174:177], v[0:15]
	s_setprio 0
	ds_read_b128 v[222:225], v231 offset:28672
	ds_read_b128 v[226:229], v231 offset:30720
	s_waitcnt lgkmcnt(2)
	s_setprio 1
	v_mfma_f32_32x32x16_bf16 v[112:127], v[214:217], v[206:209], v[112:127]
	v_mfma_f32_32x32x16_bf16 v[96:111], v[214:217], v[210:213], v[96:111]
	v_mfma_f32_32x32x16_bf16 v[80:95], v[218:221], v[206:209], v[80:95]
	v_mfma_f32_32x32x16_bf16 v[64:79], v[218:221], v[210:213], v[64:79]
	s_setprio 0
	s_waitcnt vmcnt(0) lgkmcnt(0)
	s_barrier
	ds_read_b128 v[170:173], v232 offset:49152
	ds_read_b128 v[174:177], v232 offset:51200
	ds_read_b128 v[178:181], v230 offset:49152
	ds_read_b128 v[182:185], v230 offset:51200
	ds_read_b128 v[186:189], v230 offset:53248
	ds_read_b128 v[190:193], v230 offset:55296
	s_setprio 1
	v_mfma_f32_32x32x16_bf16 v[48:63], v[222:225], v[206:209], v[48:63]
	v_mfma_f32_32x32x16_bf16 v[32:47], v[222:225], v[210:213], v[32:47]
	v_mfma_f32_32x32x16_bf16 v[16:31], v[226:229], v[206:209], v[16:31]
	v_mfma_f32_32x32x16_bf16 v[0:15], v[226:229], v[210:213], v[0:15]
	s_setprio 0
	s_add_u32 m0, s101, 0x0
	s_nop 0
	global_load_lds_dwordx4 v234, s[98:99]
	s_add_u32 m0, s101, 0x6000
	s_nop 0
	global_load_lds_dwordx4 v234, s[44:45]
	s_add_u32 m0, s101, 0x400
	s_nop 0
	global_load_lds_dwordx4 v235, s[98:99]
	s_add_u32 m0, s101, 0x6400
	s_nop 0
	global_load_lds_dwordx4 v235, s[44:45]
	s_waitcnt lgkmcnt(2)
	s_setprio 1
	v_mfma_f32_32x32x16_bf16 v[112:127], v[178:181], v[170:173], v[112:127]
	v_mfma_f32_32x32x16_bf16 v[96:111], v[178:181], v[174:177], v[96:111]
	v_mfma_f32_32x32x16_bf16 v[80:95], v[182:185], v[170:173], v[80:95]
	v_mfma_f32_32x32x16_bf16 v[64:79], v[182:185], v[174:177], v[64:79]
	s_setprio 0
	ds_read_b128 v[206:209], v233 offset:49152
	ds_read_b128 v[210:213], v233 offset:51200
	ds_read_b128 v[214:217], v231 offset:49152
	ds_read_b128 v[218:221], v231 offset:51200
	s_add_u32 m0, s101, 0x800
	s_nop 0
	global_load_lds_dwordx4 v236, s[98:99]
	s_add_u32 m0, s101, 0x6800
	s_nop 0
	global_load_lds_dwordx4 v236, s[44:45]
	s_add_u32 m0, s101, 0xc00
	s_nop 0
	global_load_lds_dwordx4 v237, s[98:99]
	s_add_u32 m0, s101, 0x6c00
	s_nop 0
	global_load_lds_dwordx4 v237, s[44:45]
	s_waitcnt lgkmcnt(4)
	s_setprio 1
	v_mfma_f32_32x32x16_bf16 v[48:63], v[186:189], v[170:173], v[48:63]
	v_mfma_f32_32x32x16_bf16 v[32:47], v[186:189], v[174:177], v[32:47]
	v_mfma_f32_32x32x16_bf16 v[16:31], v[190:193], v[170:173], v[16:31]
	v_mfma_f32_32x32x16_bf16 v[0:15], v[190:193], v[174:177], v[0:15]
	s_setprio 0
	ds_read_b128 v[222:225], v231 offset:53248
	ds_read_b128 v[226:229], v231 offset:55296
	v_xad_u32 v241, s36, v240, v238
	v_xad_u32 v242, s37, v240, v239
	s_add_u32 m0, s49, 0x0
	s_nop 0
	global_load_lds_dwordx4 v241, s[94:95]
	s_add_u32 m0, s49, 0x5fc0
	s_nop 0
	global_load_lds_dwordx4 v241, s[94:95] offset:64
	s_add_u32 m0, s49, 0x400
	s_nop 0
	global_load_lds_dwordx4 v242, s[94:95]
	s_add_u32 m0, s49, 0x63c0
	s_nop 0
	global_load_lds_dwordx4 v242, s[94:95] offset:64
	s_add_u32 s36, s36, 0x80
	s_xor_b32 s37, s36, 0x800
	s_add_u32 s98, s98, 128
	s_addc_u32 s99, s99, 0
	s_add_u32 s44, s44, 128
	s_addc_u32 s45, s45, 0
	s_waitcnt lgkmcnt(2)
	s_setprio 1
	v_mfma_f32_32x32x16_bf16 v[112:127], v[214:217], v[206:209], v[112:127]
	v_mfma_f32_32x32x16_bf16 v[96:111], v[214:217], v[210:213], v[96:111]
	v_mfma_f32_32x32x16_bf16 v[80:95], v[218:221], v[206:209], v[80:95]
	v_mfma_f32_32x32x16_bf16 v[64:79], v[218:221], v[210:213], v[64:79]
	s_setprio 0
	s_waitcnt vmcnt(0) lgkmcnt(0)
	s_barrier
	ds_read_b128 v[170:173], v232 offset:0
	ds_read_b128 v[174:177], v232 offset:2048
	ds_read_b128 v[178:181], v230 offset:0
	ds_read_b128 v[182:185], v230 offset:2048
	ds_read_b128 v[186:189], v230 offset:4096
	ds_read_b128 v[190:193], v230 offset:6144
	s_setprio 1
	v_mfma_f32_32x32x16_bf16 v[48:63], v[222:225], v[206:209], v[48:63]
	v_mfma_f32_32x32x16_bf16 v[32:47], v[222:225], v[210:213], v[32:47]
	v_mfma_f32_32x32x16_bf16 v[16:31], v[226:229], v[206:209], v[16:31]
	v_mfma_f32_32x32x16_bf16 v[0:15], v[226:229], v[210:213], v[0:15]
	s_setprio 0
	s_waitcnt lgkmcnt(2)
	s_setprio 1
	v_mfma_f32_32x32x16_bf16 v[112:127], v[178:181], v[170:173], v[112:127]
	v_mfma_f32_32x32x16_bf16 v[96:111], v[178:181], v[174:177], v[96:111]
	v_mfma_f32_32x32x16_bf16 v[80:95], v[182:185], v[170:173], v[80:95]
	v_mfma_f32_32x32x16_bf16 v[64:79], v[182:185], v[174:177], v[64:79]
	s_setprio 0
	ds_read_b128 v[206:209], v233 offset:0
	ds_read_b128 v[210:213], v233 offset:2048
	ds_read_b128 v[214:217], v231 offset:0
	ds_read_b128 v[218:221], v231 offset:2048
	s_waitcnt lgkmcnt(4)
	s_setprio 1
	v_mfma_f32_32x32x16_bf16 v[48:63], v[186:189], v[170:173], v[48:63]
	v_mfma_f32_32x32x16_bf16 v[32:47], v[186:189], v[174:177], v[32:47]
	v_mfma_f32_32x32x16_bf16 v[16:31], v[190:193], v[170:173], v[16:31]
	v_mfma_f32_32x32x16_bf16 v[0:15], v[190:193], v[174:177], v[0:15]
	s_setprio 0
	ds_read_b128 v[222:225], v231 offset:4096
	ds_read_b128 v[226:229], v231 offset:6144
	s_waitcnt lgkmcnt(2)
	s_setprio 1
	v_mfma_f32_32x32x16_bf16 v[112:127], v[214:217], v[206:209], v[112:127]
	v_mfma_f32_32x32x16_bf16 v[96:111], v[214:217], v[210:213], v[96:111]
	v_mfma_f32_32x32x16_bf16 v[80:95], v[218:221], v[206:209], v[80:95]
	v_mfma_f32_32x32x16_bf16 v[64:79], v[218:221], v[210:213], v[64:79]
	s_setprio 0
	s_sub_u32 s100, s100, 1
	s_cmp_lg_u32 s100, 0
	s_cbranch_scc1 .Lp1m_kloop
	s_waitcnt vmcnt(0) lgkmcnt(0)
	s_barrier
	ds_read_b128 v[170:173], v232 offset:24576
	ds_read_b128 v[174:177], v232 offset:26624
	ds_read_b128 v[178:181], v230 offset:24576
	ds_read_b128 v[182:185], v230 offset:26624
	ds_read_b128 v[186:189], v230 offset:28672
	ds_read_b128 v[190:193], v230 offset:30720
	s_setprio 1
	v_mfma_f32_32x32x16_bf16 v[48:63], v[222:225], v[206:209], v[48:63]
	v_mfma_f32_32x32x16_bf16 v[32:47], v[222:225], v[210:213], v[32:47]
	v_mfma_f32_32x32x16_bf16 v[16:31], v[226:229], v[206:209], v[16:31]
	v_mfma_f32_32x32x16_bf16 v[0:15], v[226:229], v[210:213], v[0:15]
	s_setprio 0
	s_add_u32 m0, s101, 0xc000
	s_nop 0
	global_load_lds_dwordx4 v234, s[98:99]
	s_add_u32 m0, s101, 0x0
	s_nop 0
	global_load_lds_dwordx4 v234, s[44:45]
	s_add_u32 m0, s101, 0xc400
	s_nop 0
	global_load_lds_dwordx4 v235, s[98:99]
	s_add_u32 m0, s101, 0x400
	s_nop 0
	global_load_lds_dwordx4 v235, s[44:45]
	s_waitcnt lgkmcnt(2)
	s_setprio 1
	v_mfma_f32_32x32x16_bf16 v[112:127], v[178:181], v[170:173], v[112:127]
	v_mfma_f32_32x32x16_bf16 v[96:111], v[178:181], v[174:177], v[96:111]
	v_mfma_f32_32x32x16_bf16 v[80:95], v[182:185], v[170:173], v[80:95]
	v_mfma_f32_32x32x16_bf16 v[64:79], v[182:185], v[174:177], v[64:79]
	s_setprio 0
	ds_read_b128 v[206:209], v233 offset:24576
	ds_read_b128 v[210:213], v233 offset:26624
	ds_read_b128 v[214:217], v231 offset:24576
	ds_read_b128 v[218:221], v231 offset:26624
	s_add_u32 m0, s101, 0xc800
	s_nop 0
	global_load_lds_dwordx4 v236, s[98:99]
	s_add_u32 m0, s101, 0x800
	s_nop 0
	global_load_lds_dwordx4 v236, s[44:45]
	s_add_u32 m0, s101, 0xcc00
	s_nop 0
	global_load_lds_dwordx4 v237, s[98:99]
	s_add_u32 m0, s101, 0xc00
	s_nop 0
	global_load_lds_dwordx4 v237, s[44:45]
	s_waitcnt lgkmcnt(4)
	s_setprio 1
	v_mfma_f32_32x32x16_bf16 v[48:63], v[186:189], v[170:173], v[48:63]
	v_mfma_f32_32x32x16_bf16 v[32:47], v[186:189], v[174:177], v[32:47]
	v_mfma_f32_32x32x16_bf16 v[16:31], v[190:193], v[170:173], v[16:31]
	v_mfma_f32_32x32x16_bf16 v[0:15], v[190:193], v[174:177], v[0:15]
	s_setprio 0
	ds_read_b128 v[222:225], v231 offset:28672
	ds_read_b128 v[226:229], v231 offset:30720
	v_xad_u32 v241, s36, v240, v238
	v_xad_u32 v242, s37, v240, v239
	s_add_u32 m0, s49, 0xc000
	s_nop 0
	global_load_lds_dwordx4 v241, s[94:95]
	s_add_u32 m0, s49, 0xffffffc0
	s_nop 0
	global_load_lds_dwordx4 v241, s[94:95] offset:64
	s_add_u32 m0, s49, 0xc400
	s_nop 0
	global_load_lds_dwordx4 v242, s[94:95]
	s_add_u32 m0, s49, 0x3c0
	s_nop 0
	global_load_lds_dwordx4 v242, s[94:95] offset:64
	s_add_u32 s36, s36, 0x80
	s_xor_b32 s37, s36, 0x800
	s_add_u32 s98, s98, 128
	s_addc_u32 s99, s99, 0
	s_add_u32 s44, s44, 128
	s_addc_u32 s45, s45, 0
	s_waitcnt lgkmcnt(2)
	s_setprio 1
	v_mfma_f32_32x32x16_bf16 v[112:127], v[214:217], v[206:209], v[112:127]
	v_mfma_f32_32x32x16_bf16 v[96:111], v[214:217], v[210:213], v[96:111]
	v_mfma_f32_32x32x16_bf16 v[80:95], v[218:221], v[206:209], v[80:95]
	v_mfma_f32_32x32x16_bf16 v[64:79], v[218:221], v[210:213], v[64:79]
	s_setprio 0
	s_waitcnt vmcnt(0) lgkmcnt(0)
	s_barrier
	ds_read_b128 v[170:173], v232 offset:49152
	ds_read_b128 v[174:177], v232 offset:51200
	ds_read_b128 v[178:181], v230 offset:49152
	ds_read_b128 v[182:185], v230 offset:51200
	ds_read_b128 v[186:189], v230 offset:53248
	ds_read_b128 v[190:193], v230 offset:55296
	s_setprio 1
	v_mfma_f32_32x32x16_bf16 v[48:63], v[222:225], v[206:209], v[48:63]
	v_mfma_f32_32x32x16_bf16 v[32:47], v[222:225], v[210:213], v[32:47]
	v_mfma_f32_32x32x16_bf16 v[16:31], v[226:229], v[206:209], v[16:31]
	v_mfma_f32_32x32x16_bf16 v[0:15], v[226:229], v[210:213], v[0:15]
	s_setprio 0
	s_waitcnt lgkmcnt(2)
	s_setprio 1
	v_mfma_f32_32x32x16_bf16 v[112:127], v[178:181], v[170:173], v[112:127]
	v_mfma_f32_32x32x16_bf16 v[96:111], v[178:181], v[174:177], v[96:111]
	v_mfma_f32_32x32x16_bf16 v[80:95], v[182:185], v[170:173], v[80:95]
	v_mfma_f32_32x32x16_bf16 v[64:79], v[182:185], v[174:177], v[64:79]
	s_setprio 0
	ds_read_b128 v[206:209], v233 offset:49152
	ds_read_b128 v[210:213], v233 offset:51200
	ds_read_b128 v[214:217], v231 offset:49152
	ds_read_b128 v[218:221], v231 offset:51200
	s_waitcnt lgkmcnt(4)
	s_setprio 1
	v_mfma_f32_32x32x16_bf16 v[48:63], v[186:189], v[170:173], v[48:63]
	v_mfma_f32_32x32x16_bf16 v[32:47], v[186:189], v[174:177], v[32:47]
	v_mfma_f32_32x32x16_bf16 v[16:31], v[190:193], v[170:173], v[16:31]
	v_mfma_f32_32x32x16_bf16 v[0:15], v[190:193], v[174:177], v[0:15]
	s_setprio 0
	ds_read_b128 v[222:225], v231 offset:53248
	ds_read_b128 v[226:229], v231 offset:55296
	s_waitcnt lgkmcnt(2)
	s_setprio 1
	v_mfma_f32_32x32x16_bf16 v[112:127], v[214:217], v[206:209], v[112:127]
	v_mfma_f32_32x32x16_bf16 v[96:111], v[214:217], v[210:213], v[96:111]
	v_mfma_f32_32x32x16_bf16 v[80:95], v[218:221], v[206:209], v[80:95]
	v_mfma_f32_32x32x16_bf16 v[64:79], v[218:221], v[210:213], v[64:79]
	s_setprio 0
	s_waitcnt vmcnt(0) lgkmcnt(0)
	s_barrier
	ds_read_b128 v[170:173], v232 offset:0
	ds_read_b128 v[174:177], v232 offset:2048
	ds_read_b128 v[178:181], v230 offset:0
	ds_read_b128 v[182:185], v230 offset:2048
	ds_read_b128 v[186:189], v230 offset:4096
	ds_read_b128 v[190:193], v230 offset:6144
	s_setprio 1
	v_mfma_f32_32x32x16_bf16 v[48:63], v[222:225], v[206:209], v[48:63]
	v_mfma_f32_32x32x16_bf16 v[32:47], v[222:225], v[210:213], v[32:47]
	v_mfma_f32_32x32x16_bf16 v[16:31], v[226:229], v[206:209], v[16:31]
	v_mfma_f32_32x32x16_bf16 v[0:15], v[226:229], v[210:213], v[0:15]
	s_setprio 0
	s_waitcnt lgkmcnt(2)
	s_setprio 1
	v_mfma_f32_32x32x16_bf16 v[112:127], v[178:181], v[170:173], v[112:127]
	v_mfma_f32_32x32x16_bf16 v[96:111], v[178:181], v[174:177], v[96:111]
	v_mfma_f32_32x32x16_bf16 v[80:95], v[182:185], v[170:173], v[80:95]
	v_mfma_f32_32x32x16_bf16 v[64:79], v[182:185], v[174:177], v[64:79]
	s_setprio 0
	ds_read_b128 v[206:209], v233 offset:0
	ds_read_b128 v[210:213], v233 offset:2048
	ds_read_b128 v[214:217], v231 offset:0
	ds_read_b128 v[218:221], v231 offset:2048
	s_waitcnt lgkmcnt(4)
	s_setprio 1
	v_mfma_f32_32x32x16_bf16 v[48:63], v[186:189], v[170:173], v[48:63]
	v_mfma_f32_32x32x16_bf16 v[32:47], v[186:189], v[174:177], v[32:47]
	v_mfma_f32_32x32x16_bf16 v[16:31], v[190:193], v[170:173], v[16:31]
	v_mfma_f32_32x32x16_bf16 v[0:15], v[190:193], v[174:177], v[0:15]
	s_setprio 0
	ds_read_b128 v[222:225], v231 offset:4096
	ds_read_b128 v[226:229], v231 offset:6144
	s_waitcnt lgkmcnt(2)
	s_setprio 1
	v_mfma_f32_32x32x16_bf16 v[112:127], v[214:217], v[206:209], v[112:127]
	v_mfma_f32_32x32x16_bf16 v[96:111], v[214:217], v[210:213], v[96:111]
	v_mfma_f32_32x32x16_bf16 v[80:95], v[218:221], v[206:209], v[80:95]
	v_mfma_f32_32x32x16_bf16 v[64:79], v[218:221], v[210:213], v[64:79]
	s_setprio 0
	s_waitcnt lgkmcnt(0)
	s_setprio 1
	v_mfma_f32_32x32x16_bf16 v[48:63], v[222:225], v[206:209], v[48:63]
	v_mfma_f32_32x32x16_bf16 v[32:47], v[222:225], v[210:213], v[32:47]
	v_mfma_f32_32x32x16_bf16 v[16:31], v[226:229], v[206:209], v[16:31]
	v_mfma_f32_32x32x16_bf16 v[0:15], v[226:229], v[210:213], v[0:15]
	s_setprio 0
	s_mul_hi_i32 s41, s42, 0x540000
	s_mul_i32 s42, s42, 0x540000
	s_add_u32 s42, s31, s42
	s_addc_u32 s43, s33, s41
	s_lshl_b32 s40, s40, 8
	s_add_u32 s42, s42, s40
	s_addc_u32 s43, s43, 0
	s_add_i32 s16, s16, s17
	s_add_i32 s47, s47, s17
	v_lshrrev_b32_e32 v170, 6, v204
	v_and_b32_e32 v171, 31, v204
	v_bfe_u32 v172, v204, 5, 1
	v_mul_u32_u24_e32 v173, 0x4400, v170
	v_mul_u32_u24_e32 v174, 544, v172
	v_lshl_add_u32 v174, v171, 2, v174
	v_add3_u32 v174, v174, v173, 32
	v_and_b32_e32 v175, 7, v204
	v_bfe_u32 v176, v204, 3, 3
	v_mul_u32_u24_e32 v177, 272, v176
	v_lshl_add_u32 v177, v175, 5, v177
	v_add3_u32 v177, v177, v173, 32
	v_lshrrev_b32_e32 v178, 1, v170
	v_and_b32_e32 v179, 1, v170
	v_lshlrev_b32_e32 v178, 7, v178
	v_lshl_add_u32 v178, v176, 1, v178
	v_mul_u32_u24_e32 v178, 0x5400, v178
	v_lshl_add_u32 v178, v179, 7, v178
	v_lshl_add_u32 v178, v175, 4, v178
	v_add_u32_e32 v179, 0x5400, v178
	v_mov_b32_e32 v180, 0x05040100
	v_mov_b32_e32 v181, 0x07060302
	s_waitcnt vmcnt(0)
	s_barrier
	v_cvt_pk_bf16_f32 v112, v112, v113
	ds_write_b32 v174, v112 offset:0
	v_cvt_pk_bf16_f32 v114, v114, v115
	ds_write_b32 v174, v114 offset:272
	v_cvt_pk_bf16_f32 v116, v116, v117
	ds_write_b32 v174, v116 offset:1088
	v_cvt_pk_bf16_f32 v118, v118, v119
	ds_write_b32 v174, v118 offset:1360
	v_cvt_pk_bf16_f32 v120, v120, v121
	ds_write_b32 v174, v120 offset:2176
	v_cvt_pk_bf16_f32 v122, v122, v123
	ds_write_b32 v174, v122 offset:2448
	v_cvt_pk_bf16_f32 v124, v124, v125
	ds_write_b32 v174, v124 offset:3264
	v_cvt_pk_bf16_f32 v126, v126, v127
	ds_write_b32 v174, v126 offset:3536
	v_cvt_pk_bf16_f32 v96, v96, v97
	ds_write_b32 v174, v96 offset:128
	v_cvt_pk_bf16_f32 v98, v98, v99
	ds_write_b32 v174, v98 offset:400
	v_cvt_pk_bf16_f32 v100, v100, v101
	ds_write_b32 v174, v100 offset:1216
	v_cvt_pk_bf16_f32 v102, v102, v103
	ds_write_b32 v174, v102 offset:1488
	v_cvt_pk_bf16_f32 v104, v104, v105
	ds_write_b32 v174, v104 offset:2304
	v_cvt_pk_bf16_f32 v106, v106, v107
	ds_write_b32 v174, v106 offset:2576
	v_cvt_pk_bf16_f32 v108, v108, v109
	ds_write_b32 v174, v108 offset:3392
	v_cvt_pk_bf16_f32 v110, v110, v111
	ds_write_b32 v174, v110 offset:3664
	v_cvt_pk_bf16_f32 v80, v80, v81
	ds_write_b32 v174, v80 offset:4352
	v_cvt_pk_bf16_f32 v82, v82, v83
	ds_write_b32 v174, v82 offset:4624
	v_cvt_pk_bf16_f32 v84, v84, v85
	ds_write_b32 v174, v84 offset:5440
	v_cvt_pk_bf16_f32 v86, v86, v87
	ds_write_b32 v174, v86 offset:5712
	v_cvt_pk_bf16_f32 v88, v88, v89
	ds_write_b32 v174, v88 offset:6528
	v_cvt_pk_bf16_f32 v90, v90, v91
	ds_write_b32 v174, v90 offset:6800
	v_cvt_pk_bf16_f32 v92, v92, v93
	ds_write_b32 v174, v92 offset:7616
	v_cvt_pk_bf16_f32 v94, v94, v95
	ds_write_b32 v174, v94 offset:7888
	v_cvt_pk_bf16_f32 v64, v64, v65
	ds_write_b32 v174, v64 offset:4480
	v_cvt_pk_bf16_f32 v66, v66, v67
	ds_write_b32 v174, v66 offset:4752
	v_cvt_pk_bf16_f32 v68, v68, v69
	ds_write_b32 v174, v68 offset:5568
	v_cvt_pk_bf16_f32 v70, v70, v71
	ds_write_b32 v174, v70 offset:5840
	v_cvt_pk_bf16_f32 v72, v72, v73
	ds_write_b32 v174, v72 offset:6656
	v_cvt_pk_bf16_f32 v74, v74, v75
	ds_write_b32 v174, v74 offset:6928
	v_cvt_pk_bf16_f32 v76, v76, v77
	ds_write_b32 v174, v76 offset:7744
	v_cvt_pk_bf16_f32 v78, v78, v79
	ds_write_b32 v174, v78 offset:8016
	v_cvt_pk_bf16_f32 v48, v48, v49
	ds_write_b32 v174, v48 offset:8704
	v_cvt_pk_bf16_f32 v50, v50, v51
	ds_write_b32 v174, v50 offset:8976
	v_cvt_pk_bf16_f32 v52, v52, v53
	ds_write_b32 v174, v52 offset:9792
	v_cvt_pk_bf16_f32 v54, v54, v55
	ds_write_b32 v174, v54 offset:10064
	v_cvt_pk_bf16_f32 v56, v56, v57
	ds_write_b32 v174, v56 offset:10880
	v_cvt_pk_bf16_f32 v58, v58, v59
	ds_write_b32 v174, v58 offset:11152
	v_cvt_pk_bf16_f32 v60, v60, v61
	ds_write_b32 v174, v60 offset:11968
	v_cvt_pk_bf16_f32 v62, v62, v63
	ds_write_b32 v174, v62 offset:12240
	v_cvt_pk_bf16_f32 v32, v32, v33
	ds_write_b32 v174, v32 offset:8832
	v_cvt_pk_bf16_f32 v34, v34, v35
	ds_write_b32 v174, v34 offset:9104
	v_cvt_pk_bf16_f32 v36, v36, v37
	ds_write_b32 v174, v36 offset:9920
	v_cvt_pk_bf16_f32 v38, v38, v39
	ds_write_b32 v174, v38 offset:10192
	v_cvt_pk_bf16_f32 v40, v40, v41
	ds_write_b32 v174, v40 offset:11008
	v_cvt_pk_bf16_f32 v42, v42, v43
	ds_write_b32 v174, v42 offset:11280
	v_cvt_pk_bf16_f32 v44, v44, v45
	ds_write_b32 v174, v44 offset:12096
	v_cvt_pk_bf16_f32 v46, v46, v47
	ds_write_b32 v174, v46 offset:12368
	v_cvt_pk_bf16_f32 v16, v16, v17
	ds_write_b32 v174, v16 offset:13056
	v_cvt_pk_bf16_f32 v18, v18, v19
	ds_write_b32 v174, v18 offset:13328
	v_cvt_pk_bf16_f32 v20, v20, v21
	ds_write_b32 v174, v20 offset:14144
	v_cvt_pk_bf16_f32 v22, v22, v23
	ds_write_b32 v174, v22 offset:14416
	v_cvt_pk_bf16_f32 v24, v24, v25
	ds_write_b32 v174, v24 offset:15232
	v_cvt_pk_bf16_f32 v26, v26, v27
	ds_write_b32 v174, v26 offset:15504
	v_cvt_pk_bf16_f32 v28, v28, v29
	ds_write_b32 v174, v28 offset:16320
	v_cvt_pk_bf16_f32 v30, v30, v31
	ds_write_b32 v174, v30 offset:16592
	v_cvt_pk_bf16_f32 v0, v0, v1
	ds_write_b32 v174, v0 offset:13184
	v_cvt_pk_bf16_f32 v2, v2, v3
	ds_write_b32 v174, v2 offset:13456
	v_cvt_pk_bf16_f32 v4, v4, v5
	ds_write_b32 v174, v4 offset:14272
	v_cvt_pk_bf16_f32 v6, v6, v7
	ds_write_b32 v174, v6 offset:14544
	v_cvt_pk_bf16_f32 v8, v8, v9
	ds_write_b32 v174, v8 offset:15360
	v_cvt_pk_bf16_f32 v10, v10, v11
	ds_write_b32 v174, v10 offset:15632
	v_cvt_pk_bf16_f32 v12, v12, v13
	ds_write_b32 v174, v12 offset:16448
	v_cvt_pk_bf16_f32 v14, v14, v15
	ds_write_b32 v174, v14 offset:16720
	s_cmp_ge_i32 s16, s22
	s_cselect_b64 s[40:41], -1, 0
	s_waitcnt lgkmcnt(0)
	ds_read_b128 v[182:185], v177 offset:0
	ds_read_b128 v[186:189], v177 offset:16
	ds_read_b128 v[190:193], v177 offset:2176
	ds_read_b128 v[194:197], v177 offset:2192
	s_waitcnt lgkmcnt(2)
	v_perm_b32 v198, v183, v182, v180
	v_perm_b32 v199, v185, v184, v180
	v_perm_b32 v200, v187, v186, v180
	v_perm_b32 v201, v189, v188, v180
	v_perm_b32 v206, v183, v182, v181
	v_perm_b32 v207, v185, v184, v181
	v_perm_b32 v208, v187, v186, v181
	v_perm_b32 v209, v189, v188, v181
	global_store_dwordx4 v178, v[198:201], s[42:43]
	global_store_dwordx4 v179, v[206:209], s[42:43]
	s_add_u32 s42, s42, 0x54000
	s_addc_u32 s43, s43, 0
	s_nop 1
	ds_read_b128 v[182:185], v177 offset:4352
	ds_read_b128 v[186:189], v177 offset:4368
	s_waitcnt lgkmcnt(2)
	v_perm_b32 v198, v191, v190, v180
	v_perm_b32 v199, v193, v192, v180
	v_perm_b32 v200, v195, v194, v180
	v_perm_b32 v201, v197, v196, v180
	v_perm_b32 v206, v191, v190, v181
	v_perm_b32 v207, v193, v192, v181
	v_perm_b32 v208, v195, v194, v181
	v_perm_b32 v209, v197, v196, v181
	global_store_dwordx4 v178, v[198:201], s[42:43]
	global_store_dwordx4 v179, v[206:209], s[42:43]
	s_add_u32 s42, s42, 0x54000
	s_addc_u32 s43, s43, 0
	s_nop 1
	ds_read_b128 v[190:193], v177 offset:6528
	ds_read_b128 v[194:197], v177 offset:6544
	s_waitcnt lgkmcnt(2)
	v_perm_b32 v198, v183, v182, v180
	v_perm_b32 v199, v185, v184, v180
	v_perm_b32 v200, v187, v186, v180
	v_perm_b32 v201, v189, v188, v180
	v_perm_b32 v206, v183, v182, v181
	v_perm_b32 v207, v185, v184, v181
	v_perm_b32 v208, v187, v186, v181
	v_perm_b32 v209, v189, v188, v181
	global_store_dwordx4 v178, v[198:201], s[42:43]
	global_store_dwordx4 v179, v[206:209], s[42:43]
	s_add_u32 s42, s42, 0x54000
	s_addc_u32 s43, s43, 0
	s_nop 1
	ds_read_b128 v[182:185], v177 offset:8704
	ds_read_b128 v[186:189], v177 offset:8720
	s_waitcnt lgkmcnt(2)
	v_perm_b32 v198, v191, v190, v180
	v_perm_b32 v199, v193, v192, v180
	v_perm_b32 v200, v195, v194, v180
	v_perm_b32 v201, v197, v196, v180
	v_perm_b32 v206, v191, v190, v181
	v_perm_b32 v207, v193, v192, v181
	v_perm_b32 v208, v195, v194, v181
	v_perm_b32 v209, v197, v196, v181
	global_store_dwordx4 v178, v[198:201], s[42:43]
	global_store_dwordx4 v179, v[206:209], s[42:43]
	s_add_u32 s42, s42, 0x54000
	s_addc_u32 s43, s43, 0
	s_nop 1
	ds_read_b128 v[190:193], v177 offset:10880
	ds_read_b128 v[194:197], v177 offset:10896
	s_waitcnt lgkmcnt(2)
	v_perm_b32 v198, v183, v182, v180
	v_perm_b32 v199, v185, v184, v180
	v_perm_b32 v200, v187, v186, v180
	v_perm_b32 v201, v189, v188, v180
	v_perm_b32 v206, v183, v182, v181
	v_perm_b32 v207, v185, v184, v181
	v_perm_b32 v208, v187, v186, v181
	v_perm_b32 v209, v189, v188, v181
	global_store_dwordx4 v178, v[198:201], s[42:43]
	global_store_dwordx4 v179, v[206:209], s[42:43]
	s_add_u32 s42, s42, 0x54000
	s_addc_u32 s43, s43, 0
	s_nop 1
	ds_read_b128 v[182:185], v177 offset:13056
	ds_read_b128 v[186:189], v177 offset:13072
	s_waitcnt lgkmcnt(2)
	v_perm_b32 v198, v191, v190, v180
	v_perm_b32 v199, v193, v192, v180
	v_perm_b32 v200, v195, v194, v180
	v_perm_b32 v201, v197, v196, v180
	v_perm_b32 v206, v191, v190, v181
	v_perm_b32 v207, v193, v192, v181
	v_perm_b32 v208, v195, v194, v181
	v_perm_b32 v209, v197, v196, v181
	global_store_dwordx4 v178, v[198:201], s[42:43]
	global_store_dwordx4 v179, v[206:209], s[42:43]
	s_add_u32 s42, s42, 0x54000
	s_addc_u32 s43, s43, 0
	s_nop 1
	ds_read_b128 v[190:193], v177 offset:15232
	ds_read_b128 v[194:197], v177 offset:15248
	s_waitcnt lgkmcnt(2)
	v_perm_b32 v198, v183, v182, v180
	v_perm_b32 v199, v185, v184, v180
	v_perm_b32 v200, v187, v186, v180
	v_perm_b32 v201, v189, v188, v180
	v_perm_b32 v206, v183, v182, v181
	v_perm_b32 v207, v185, v184, v181
	v_perm_b32 v208, v187, v186, v181
	v_perm_b32 v209, v189, v188, v181
	global_store_dwordx4 v178, v[198:201], s[42:43]
	global_store_dwordx4 v179, v[206:209], s[42:43]
	s_add_u32 s42, s42, 0x54000
	s_addc_u32 s43, s43, 0
	s_nop 1
	s_waitcnt lgkmcnt(0)
	s_barrier
	v_perm_b32 v198, v191, v190, v180
	v_perm_b32 v199, v193, v192, v180
	v_perm_b32 v200, v195, v194, v180
	v_perm_b32 v201, v197, v196, v180
	v_perm_b32 v206, v191, v190, v181
	v_perm_b32 v207, v193, v192, v181
	v_perm_b32 v208, v195, v194, v181
	v_perm_b32 v209, v197, v196, v181
	global_store_dwordx4 v178, v[198:201], s[42:43]
	global_store_dwordx4 v179, v[206:209], s[42:43]
	s_branch .LBB0_126
